# P3: sample-attention units both before (even blocks) or both after (odd blocks) the prompt units, instead of thirds
# baseline (speedup 1.0000x reference)
.LBB0_1534:
	s_cmp_gt_i32 s28, 3
	s_cselect_b64 s[0:1], -1, 0
	s_cmp_lt_i32 s29, 4
	s_cselect_b64 s[2:3], -1, 0
	s_or_b64 s[0:1], s[0:1], s[2:3]
	s_and_b64 vcc, exec, s[0:1]
	s_cbranch_vccnz .LBB0_2366
	v_readlane_b32 s0, v251, 4
	s_cmpk_lg_i32 s0, 0x100
	s_cbranch_scc1 .LBB0_2316
	v_readlane_b32 s4, v251, 44
	v_readlane_b32 s6, v251, 46
	v_readlane_b32 s7, v251, 47
	s_add_u32 s54, s6, 0x9600000
	s_mul_hi_i32 s0, s89, 0x55555556
	s_addc_u32 s55, s7, 0
	s_lshr_b32 s1, s0, 31
	s_add_i32 s0, s0, s1
	s_mul_i32 s0, s0, 3
	s_and_b32 s2, s89, 1
	s_xor_b32 s2, s2, 1
	s_lshl_b32 s2, s2, 1
	v_readlane_b32 s5, v251, 45
	s_cmp_lt_i32 s2, 2
	v_readlane_b32 s8, v251, 48
	v_readlane_b32 s9, v251, 49
	v_readlane_b32 s10, v251, 50
	v_readlane_b32 s11, v251, 51
	s_cbranch_scc1 .LBB0_1539
	v_and_b32_e32 v100, 31, v0
	v_lshlrev_b32_e32 v1, 4, v198
	s_cbranch_execz .LBB0_1540
	s_waitcnt lgkmcnt(0)
	s_mov_b32 s38, s89
	s_branch .LBB0_1884
